# adds: prep1 row loads hoisted (one HBM round trip per token), GLA combine loop software-pipelined with next-row prefetch and loop-invariant gnorm loads hoisted, Plan-Q norm parameter loads issued toge
# speedup vs baseline: 1.0091x; 1.0024x over previous
.Lq_md_Q1_p0:
	s_mul_i32 s8, s1, 0x9000
	s_add_u32 s2, s2, s8
	s_addc_u32 s3, s3, 0
	global_load_dwordx4 v[100:103], v84, s[2:3]
	global_load_dwordx4 v[104:107], v84, s[2:3] offset:1024
	global_load_dwordx4 v[108:111], v84, s[2:3] offset:2048
	global_load_dwordx4 v[112:115], v84, s[2:3] offset:3072
	s_add_u32 s2, s2, 0x1000
	s_addc_u32 s3, s3, 0
	global_load_dwordx4 v[116:119], v84, s[2:3]
	global_load_dwordx4 v[120:123], v84, s[2:3] offset:1024
	global_load_dwordx4 v[124:127], v84, s[2:3] offset:2048
	global_load_dwordx4 v[128:131], v84, s[2:3] offset:3072
	s_waitcnt vmcnt(0)
	v_add_f32_e32 v116, 1.0, v116
	v_add_f32_e32 v117, 1.0, v117
	v_add_f32_e32 v118, 1.0, v118
	v_add_f32_e32 v119, 1.0, v119
	v_add_f32_e32 v120, 1.0, v120
	v_add_f32_e32 v121, 1.0, v121
	v_add_f32_e32 v122, 1.0, v122
	v_add_f32_e32 v123, 1.0, v123
	v_add_f32_e32 v124, 1.0, v124
	v_add_f32_e32 v125, 1.0, v125
	v_add_f32_e32 v126, 1.0, v126
	v_add_f32_e32 v127, 1.0, v127
	v_add_f32_e32 v128, 1.0, v128
	v_add_f32_e32 v129, 1.0, v129
	v_add_f32_e32 v130, 1.0, v130
	v_add_f32_e32 v131, 1.0, v131
	v_mul_f32_e32 v68, v68, v116
	v_mul_f32_e32 v69, v69, v117
	v_mul_f32_e32 v70, v70, v118
	v_mul_f32_e32 v71, v71, v119
	v_mul_f32_e32 v72, v72, v120
	v_mul_f32_e32 v73, v73, v121
	v_mul_f32_e32 v74, v74, v122
	v_mul_f32_e32 v75, v75, v123
	v_mul_f32_e32 v76, v76, v124
	v_mul_f32_e32 v77, v77, v125
	v_mul_f32_e32 v78, v78, v126
	v_mul_f32_e32 v79, v79, v127
	v_mul_f32_e32 v80, v80, v128
	v_mul_f32_e32 v81, v81, v129
	v_mul_f32_e32 v82, v82, v130
	v_mul_f32_e32 v83, v83, v131

.LBB0_558:
	v_lshl_add_u64 v[36:37], s[50:51], 0, v[34:35]
	v_add_co_u32_e32 v38, vcc, 0xe8a2000, v36
	v_lshl_add_u64 v[58:59], s[50:51], 0, v[32:33]
	s_nop 0
	v_addc_co_u32_e32 v39, vcc, 0, v37, vcc
	v_mov_b32_e32 v108, v38
	v_mov_b32_e32 v109, v39
	global_load_dword v39, v[38:39], off nt
	s_mov_b32 s8, 0x3b800000
	global_load_dwordx2 v[58:59], v[58:59], off nt
	global_load_dword v100, v[108:109], off offset:256
	global_load_dword v101, v[108:109], off offset:320 nt
	global_load_dword v102, v[108:109], off offset:576
	v_lshl_add_u64 v[110:111], s[50:51], 0, v[30:31]
	global_load_dwordx4 v[104:107], v[110:111], off nt
	s_brev_b32 s9, 60
	v_lshl_add_u64 v[42:43], s[50:51], 0, v[28:29]
	s_waitcnt vmcnt(5)
	v_lshlrev_b32_e32 v38, 16, v39
	v_and_b32_e32 v39, 0xffff0000, v39
	s_waitcnt vmcnt(4)
	v_and_b32_e32 v61, 0xffff0000, v59
	v_and_b32_e32 v63, 0xffff0000, v58
	v_lshlrev_b32_e32 v60, 16, v59
	v_lshlrev_b32_e32 v62, 16, v58
	v_mov_b32_e32 v64, v63
	v_mov_b32_e32 v65, v61
	v_mov_b32_e32 v58, v62
	v_mov_b32_e32 v59, v60
	v_pk_mul_f32 v[64:65], v[64:65], v[64:65]
	v_pk_mul_f32 v[40:41], v[38:39], v[38:39]
	v_pk_fma_f32 v[58:59], v[58:59], v[58:59], v[64:65]
	v_mov_b32_e32 v65, v40
	v_mov_b32_e32 v64, v58
	v_mov_b32_e32 v40, v59
	v_pk_add_f32 v[40:41], v[64:65], v[40:41]
	ds_bpermute_b32 v59, v48, v41
	ds_bpermute_b32 v58, v48, v40
	s_waitcnt lgkmcnt(0)
	v_pk_add_f32 v[40:41], v[40:41], v[58:59]
	ds_bpermute_b32 v59, v49, v41
	ds_bpermute_b32 v58, v49, v40
	s_waitcnt lgkmcnt(0)
	v_pk_add_f32 v[40:41], v[40:41], v[58:59]
	ds_bpermute_b32 v59, v50, v41
	ds_bpermute_b32 v58, v50, v40
	s_waitcnt lgkmcnt(0)
	v_pk_add_f32 v[40:41], v[40:41], v[58:59]
	ds_bpermute_b32 v59, v51, v41
	ds_bpermute_b32 v58, v51, v40
	s_waitcnt lgkmcnt(0)
	v_pk_add_f32 v[40:41], v[40:41], v[58:59]
	ds_bpermute_b32 v59, v52, v41
	ds_bpermute_b32 v58, v52, v40
	s_waitcnt lgkmcnt(0)
	v_pk_add_f32 v[40:41], v[40:41], v[58:59]
	ds_bpermute_b32 v59, v53, v41
	ds_bpermute_b32 v58, v53, v40
	s_waitcnt lgkmcnt(0)
	v_pk_add_f32 v[40:41], v[40:41], v[58:59]
	s_nop 0
	v_pk_fma_f32 v[40:41], v[40:41], s[8:9], v[206:207] op_sel_hi:[1,1,0]
	s_nop 0
	v_mul_f32_e32 v57, 0x4b800000, v41
	v_cmp_gt_f32_e64 s[8:9], s97, v41
	v_cmp_gt_f32_e32 vcc, s97, v40
	s_nop 0
	v_cndmask_b32_e64 v41, v41, v57, s[8:9]
	v_rsq_f32_e32 v41, v41
	s_nop 0
	v_mul_f32_e32 v57, 0x45800000, v41
	v_cndmask_b32_e64 v58, v41, v57, s[8:9]
	v_pk_mul_f32 v[38:39], v[58:59], v[38:39] op_sel_hi:[0,1]
	v_pk_mul_f32 v[38:39], v[14:15], v[38:39]
	s_nop 0
	v_cvt_pk_bf16_f32 v38, v38, v39
	global_store_dword v[42:43], v38, off
	v_mul_f32_e32 v38, 0x4b800000, v40
	v_cndmask_b32_e32 v38, v40, v38, vcc
	v_rsq_f32_e32 v38, v38
	s_nop 0
	v_mul_f32_e32 v39, 0x45800000, v38
	v_cndmask_b32_e32 v38, v38, v39, vcc
	v_pk_mul_f32 v[40:41], v[38:39], v[62:63] op_sel_hi:[0,1]
	v_pk_mul_f32 v[38:39], v[38:39], v[60:61] op_sel_hi:[0,1]
	v_pk_mul_f32 v[40:41], v[2:3], v[40:41]
	v_pk_mul_f32 v[38:39], v[4:5], v[38:39]
	v_cvt_pk_bf16_f32 v40, v40, v41
	v_cvt_pk_bf16_f32 v41, v38, v39
	v_lshl_add_u64 v[38:39], s[50:51], 0, v[26:27]
	global_store_dwordx2 v[38:39], v[40:41], off
	v_mov_b32_e32 v38, 0
	v_mov_b32_e32 v39, 0
	s_and_saveexec_b64 s[8:9], s[0:1]
	s_cbranch_execz .LBB0_560
	s_waitcnt vmcnt(5)
	v_mov_b32_e32 v39, v100
	v_lshlrev_b32_e32 v38, 16, v39
	v_and_b32_e32 v39, 0xffff0000, v39
.LBB0_560:
	s_or_b64 exec, exec, s[8:9]
	v_pk_mul_f32 v[40:41], v[38:39], v[38:39]
	v_cndmask_b32_e64 v42, 0, 1, s[14:15]
	v_add_f32_e32 v40, v40, v41
	ds_bpermute_b32 v41, v48, v40
	v_cmp_ne_u32_e64 s[8:9], 1, v42
	s_waitcnt lgkmcnt(0)
	v_add_f32_e32 v40, v40, v41
	ds_bpermute_b32 v41, v49, v40
	s_waitcnt lgkmcnt(0)
	v_add_f32_e32 v40, v40, v41
	ds_bpermute_b32 v41, v50, v40
	s_waitcnt lgkmcnt(0)
	v_add_f32_e32 v40, v40, v41
	ds_bpermute_b32 v41, v51, v40
	s_waitcnt lgkmcnt(0)
	v_add_f32_e32 v40, v40, v41
	ds_bpermute_b32 v41, v52, v40
	s_waitcnt lgkmcnt(0)
	v_add_f32_e32 v40, v40, v41
	ds_bpermute_b32 v41, v53, v40
	s_waitcnt vmcnt(2)
	s_and_saveexec_b64 s[14:15], s[0:1]
	s_cbranch_execz .LBB0_564
	global_load_dwordx2 v[42:43], v[18:19], off
	s_waitcnt lgkmcnt(0)
	v_add_f32_e32 v40, v40, v41
	v_fmamk_f32 v40, v40, 0x3d000000, v206
	v_mul_f32_e32 v41, 0x4b800000, v40
	v_cmp_gt_f32_e32 vcc, s97, v40
	s_nop 1
	v_cndmask_b32_e32 v40, v40, v41, vcc
	v_rsq_f32_e32 v40, v40
	s_nop 0
	v_mul_f32_e32 v41, 0x45800000, v40
	v_cndmask_b32_e32 v40, v40, v41, vcc
	s_and_b64 vcc, exec, s[8:9]
	s_waitcnt vmcnt(0)
	v_pk_mul_f32 v[40:41], v[40:41], v[42:43] op_sel_hi:[0,1]
	v_pk_mul_f32 v[38:39], v[38:39], v[40:41]
	s_cbranch_vccnz .LBB0_563
	v_cndmask_b32_e64 v40, v56, v55, s[2:3]
	v_mul_f32_e32 v40, v46, v40
	v_mul_f32_e32 v41, 0.15915494, v40
	v_sin_f32_e32 v40, v41
	v_cos_f32_e32 v42, v41
	v_pk_mul_f32 v[40:41], v[40:41], v[38:39] op_sel:[0,1] op_sel_hi:[0,0]
	v_pk_mul_f32 v[58:59], v[42:43], v[38:39] op_sel_hi:[0,1]
	v_pk_fma_f32 v[38:39], v[42:43], v[38:39], v[40:41] op_sel_hi:[0,1,1]
	v_sub_f32_e32 v38, v58, v40

.LBB0_564:
	s_or_b64 exec, exec, s[14:15]
	v_mov_b32_e32 v39, v101
	v_lshlrev_b32_e32 v38, 16, v39
	v_and_b32_e32 v39, 0xffff0000, v39
	s_waitcnt lgkmcnt(0)
	v_pk_mul_f32 v[40:41], v[38:39], v[38:39]
	s_nop 0
	v_add_f32_e32 v40, v40, v41
	ds_bpermute_b32 v41, v48, v40
	s_waitcnt lgkmcnt(0)
	v_add_f32_e32 v40, v40, v41
	ds_bpermute_b32 v41, v49, v40
	s_waitcnt lgkmcnt(0)
	v_add_f32_e32 v40, v40, v41
	ds_bpermute_b32 v41, v50, v40
	s_waitcnt lgkmcnt(0)
	v_add_f32_e32 v40, v40, v41
	ds_bpermute_b32 v41, v51, v40
	s_waitcnt lgkmcnt(0)
	v_add_f32_e32 v40, v40, v41
	ds_bpermute_b32 v41, v52, v40
	s_waitcnt lgkmcnt(0)
	v_add_f32_e32 v40, v40, v41
	v_fmamk_f32 v40, v40, 0x3c800000, v206
	v_mul_f32_e32 v41, 0x4b800000, v40
	v_cmp_gt_f32_e32 vcc, s97, v40
	s_nop 1
	v_cndmask_b32_e32 v40, v40, v41, vcc
	v_rsq_f32_e32 v40, v40
	s_nop 0
	v_mul_f32_e32 v41, 0x45800000, v40
	v_cndmask_b32_e32 v40, v40, v41, vcc
	v_pk_mul_f32 v[40:41], v[16:17], v[40:41] op_sel_hi:[1,0]
	s_and_b64 vcc, exec, s[8:9]
	v_pk_mul_f32 v[38:39], v[40:41], v[38:39]
	s_cbranch_vccnz .LBB0_566
	v_cndmask_b32_e64 v40, v56, v55, s[4:5]
	v_mul_f32_e32 v40, v47, v40
	v_mul_f32_e32 v41, 0.15915494, v40
	v_sin_f32_e32 v40, v41
	v_cos_f32_e32 v42, v41
	v_pk_mul_f32 v[40:41], v[40:41], v[38:39] op_sel:[0,1] op_sel_hi:[0,0]
	v_pk_mul_f32 v[58:59], v[42:43], v[38:39] op_sel_hi:[0,1]
	v_pk_fma_f32 v[38:39], v[42:43], v[38:39], v[40:41] op_sel_hi:[0,1,1]
	v_sub_f32_e32 v38, v58, v40
.LBB0_566:
	v_lshl_or_b32 v42, s10, 1, v54
	v_mov_b32_e32 v40, s11
	v_mov_b32_e32 v41, v0
	v_mad_i64_i32 v[40:41], s[10:11], v42, s64, v[40:41]
	v_cvt_pk_bf16_f32 v42, v38, v39
	v_lshlrev_b64 v[38:39], 7, v[40:41]
	s_mov_b32 s10, 0xe8a2000
	v_lshl_or_b32 v38, v20, 1, v38
	v_add_co_u32_e32 v36, vcc, s10, v36
	v_lshl_add_u64 v[40:41], s[52:53], 0, v[38:39]
	s_nop 0
	v_addc_co_u32_e32 v37, vcc, 0, v37, vcc
	global_store_dword v[40:41], v42, off
	v_mov_b32_e32 v40, v102
	v_readlane_b32 s10, v253, 3
	v_readlane_b32 s11, v253, 4
	s_nop 1
	v_lshl_add_u64 v[36:37], s[10:11], 0, v[38:39]
	global_store_dword v[36:37], v40, off
	v_mov_b32_e32 v36, v104
	v_mov_b32_e32 v37, v105
	v_mov_b32_e32 v38, v106
	v_mov_b32_e32 v39, v107
	v_lshlrev_b32_e32 v58, 16, v36
	v_and_b32_e32 v59, 0xffff0000, v36
	v_pk_mul_f32 v[60:61], v[58:59], v[58:59]
	v_lshlrev_b32_e32 v36, 16, v37
	v_and_b32_e32 v37, 0xffff0000, v37
	v_pk_mul_f32 v[62:63], v[36:37], v[36:37]
	v_add_f32_e32 v57, v60, v61
	v_lshlrev_b32_e32 v64, 16, v38
	v_and_b32_e32 v65, 0xffff0000, v38
	v_add_f32_e32 v57, v62, v57
	v_and_b32_e32 v42, 0xffff0000, v39
	v_lshlrev_b32_e32 v43, 16, v39
	v_pk_mul_f32 v[38:39], v[64:65], v[64:65]
	v_add_f32_e32 v57, v63, v57
	v_add_f32_e32 v38, v38, v57
	v_pk_mul_f32 v[40:41], v[42:43], v[42:43]
	v_add_f32_e32 v38, v39, v38
	v_add_f32_e32 v38, v41, v38
	v_add_f32_e32 v38, v40, v38
	ds_bpermute_b32 v39, v48, v38
	s_waitcnt lgkmcnt(0)
	v_add_f32_e32 v38, v38, v39
	ds_bpermute_b32 v39, v49, v38
	s_waitcnt lgkmcnt(0)
	v_add_f32_e32 v38, v38, v39
	ds_bpermute_b32 v39, v50, v38
	s_waitcnt lgkmcnt(0)
	v_add_f32_e32 v38, v38, v39
	v_fmamk_f32 v38, v38, 0x3c800000, v206
	v_cmp_gt_f32_e32 vcc, s97, v38
	v_mul_f32_e32 v39, 0x4b800000, v38
	s_nop 0
	v_cndmask_b32_e32 v38, v38, v39, vcc
	v_rsq_f32_e32 v38, v38
	s_nop 0
	v_mul_f32_e32 v39, 0x45800000, v38
	v_cndmask_b32_e32 v60, v38, v39, vcc
	v_pk_mul_f32 v[38:39], v[10:11], v[60:61] op_sel_hi:[1,0]
	s_and_b64 vcc, exec, s[8:9]
	v_pk_mul_f32 v[40:41], v[38:39], v[58:59]
	v_pk_mul_f32 v[38:39], v[12:13], v[60:61] op_sel_hi:[1,0]
	v_pk_mul_f32 v[58:59], v[8:9], v[60:61] op_sel_hi:[1,0]
	v_pk_mul_f32 v[38:39], v[38:39], v[36:37]
	v_pk_mul_f32 v[36:37], v[6:7], v[60:61] op_sel_hi:[1,0]
	v_pk_mul_f32 v[42:43], v[58:59], v[42:43] op_sel:[0,1] op_sel_hi:[1,0]
	v_pk_mul_f32 v[36:37], v[36:37], v[64:65]
	s_cbranch_vccnz .LBB0_553
	v_cndmask_b32_e64 v55, v56, v55, s[6:7]
	v_mul_f32_e32 v56, v1, v55
	v_mul_f32_e32 v57, 0.15915494, v56
	v_sin_f32_e32 v56, v57
	v_cos_f32_e32 v58, v57
	v_pk_mul_f32 v[56:57], v[56:57], v[40:41] op_sel:[0,1] op_sel_hi:[0,0]
	v_pk_mul_f32 v[60:61], v[58:59], v[40:41] op_sel_hi:[0,1]
	v_pk_fma_f32 v[40:41], v[58:59], v[40:41], v[56:57] op_sel_hi:[0,1,1]
	v_mul_f32_e32 v40, v21, v55
	v_mul_f32_e32 v57, 0.15915494, v40
	v_sin_f32_e32 v40, v57
	v_cos_f32_e32 v58, v57
	v_pk_mul_f32 v[62:63], v[40:41], v[38:39] op_sel:[0,1] op_sel_hi:[0,0]
	v_pk_fma_f32 v[64:65], v[58:59], v[38:39], v[62:63] op_sel_hi:[0,1,1] neg_lo:[0,0,1] neg_hi:[0,0,1]
	v_pk_fma_f32 v[38:39], v[58:59], v[38:39], v[62:63] op_sel_hi:[0,1,1]
	v_mul_f32_e32 v38, v44, v55
	v_mul_f32_e32 v40, 0.15915494, v38
	v_sin_f32_e32 v38, v40
	v_cos_f32_e32 v40, v40
	v_pk_mul_f32 v[58:59], v[38:39], v[36:37] op_sel:[0,1] op_sel_hi:[0,0]
	v_pk_fma_f32 v[62:63], v[40:41], v[36:37], v[58:59] op_sel_hi:[0,1,1] neg_lo:[0,0,1] neg_hi:[0,0,1]
	v_pk_fma_f32 v[36:37], v[40:41], v[36:37], v[58:59] op_sel_hi:[0,1,1]
	v_mul_f32_e32 v36, v45, v55
	v_mul_f32_e32 v36, 0.15915494, v36
	v_sin_f32_e32 v59, v36
	v_cos_f32_e32 v58, v36
	v_sub_f32_e32 v40, v60, v56
	v_mov_b32_e32 v38, v64
	v_mul_f32_e32 v36, v59, v43
	v_pk_fma_f32 v[66:67], v[58:59], v[42:43], v[36:37] op_sel_hi:[1,1,0] neg_lo:[0,0,1] neg_hi:[0,0,1]
	v_mov_b32_e32 v68, v59
	v_mov_b32_e32 v69, v58
	v_mul_f32_e32 v36, v58, v43
	v_pk_fma_f32 v[58:59], v[68:69], v[42:43], v[36:37] op_sel_hi:[1,1,0]
	v_mov_b32_e32 v36, v62
	v_mov_b32_e32 v42, v66
	v_mov_b32_e32 v43, v58
	s_branch .LBB0_553

.LBB0_1386:
	s_or_b64 exec, exec, s[0:1]
	s_waitcnt lgkmcnt(0)
	v_mov_b32_e32 v2, v207
	s_barrier
	v_readlane_b32 s1, v252, 34
	v_readfirstlane_b32 s0, v2
	s_ashr_i32 s0, s0, 6
	s_add_i32 s0, s0, s1
	s_cmp_gt_i32 s0, 0xffff
	s_cbranch_scc1 .LBB0_1389
	v_cmp_lt_i32_e32 vcc, v228, v235
	s_ashr_i32 s1, s0, 31
	s_lshl_b64 s[2:3], s[0:1], 13
	v_cndmask_b32_e32 v1, v233, v228, vcc
	v_cmp_lt_i32_e32 vcc, v234, v235
	s_add_u32 s2, s50, s2
	s_addc_u32 s3, s51, s3
	v_cndmask_b32_e32 v3, v233, v234, vcc
	v_cmp_lt_i32_e32 vcc, v240, v235
	v_lshlrev_b32_e32 v30, 2, v3
	s_lshl_b64 s[4:5], s[0:1], 11
	v_cndmask_b32_e32 v3, v233, v240, vcc
	v_cmp_lt_i32_e32 vcc, v245, v235
	v_lshlrev_b32_e32 v31, 2, v3
	v_mov_b32_e32 v5, v0
	v_cndmask_b32_e32 v3, v233, v245, vcc
	v_lshlrev_b32_e32 v32, 2, v3
	v_lshlrev_b32_e32 v3, 6, v2
	v_and_b32_e32 v4, 0x3c0, v3
	v_and_b32_e32 v2, 63, v2
	s_add_u32 s4, s50, s4
	v_lshlrev_b32_e32 v1, 2, v1
	s_waitcnt vmcnt(0)
	v_lshl_add_u64 v[18:19], s[44:45], 0, v[4:5]
	v_lshlrev_b32_e32 v20, 5, v2
	v_mov_b32_e32 v21, v0
	s_addc_u32 s5, s51, s5
	v_lshl_add_u64 v[124:125], s[4:5], 0, v[20:21]
	s_mov_b64 s[6:7], 0x64a2000
	v_lshl_add_u64 v[126:127], v[124:125], 0, s[6:7]
	s_mov_b64 s[6:7], 0x2f8a2000
	v_lshl_add_u64 v[128:129], v[124:125], 0, s[6:7]
	global_load_dwordx4 v[100:103], v[126:127], off
	global_load_dwordx4 v[104:107], v[126:127], off offset:16
	global_load_dwordx4 v[108:111], v[128:129], off
	global_load_dwordx4 v[112:115], v[128:129], off offset:16
	v_lshl_add_u64 v[124:125], s[2:3], 0, v[20:21]
	s_mov_b64 s[6:7], 0xe8a3800
	v_lshl_add_u64 v[124:125], v[124:125], 0, s[6:7]
	global_load_dwordx4 v[116:119], v[124:125], off
	global_load_dwordx4 v[120:123], v[124:125], off offset:16
	global_load_dwordx4 v[132:135], v[18:19], off offset:48
	global_load_dwordx4 v[136:139], v[18:19], off offset:32
	global_load_dwordx4 v[140:143], v[18:19], off offset:16
	global_load_dwordx4 v[144:147], v[18:19], off
	s_waitcnt vmcnt(0)
.LBB0_1388:
	s_nop 0
	v_lshl_add_u64 v[2:3], s[4:5], 0, v[20:21]
	v_add_co_u32_e32 v22, vcc, 0x64a2000, v2
	s_nop 1
	v_addc_co_u32_e32 v23, vcc, 0, v3, vcc
	s_waitcnt vmcnt(2)
	v_mov_b32_e32 v6, v100
	v_mov_b32_e32 v7, v101
	v_mov_b32_e32 v8, v102
	v_mov_b32_e32 v9, v103
	v_mov_b32_e32 v34, v104
	v_mov_b32_e32 v35, v105
	v_mov_b32_e32 v36, v106
	v_mov_b32_e32 v37, v107
	v_mov_b32_e32 v10, v108
	v_mov_b32_e32 v11, v109
	v_mov_b32_e32 v12, v110
	v_mov_b32_e32 v13, v111
	v_mov_b32_e32 v38, v112
	v_mov_b32_e32 v39, v113
	v_mov_b32_e32 v40, v114
	v_mov_b32_e32 v41, v115
	v_mov_b32_e32 v14, v116
	v_mov_b32_e32 v15, v117
	v_mov_b32_e32 v16, v118
	v_mov_b32_e32 v17, v119
	v_mov_b32_e32 v2, v120
	v_mov_b32_e32 v3, v121
	v_mov_b32_e32 v4, v122
	v_mov_b32_e32 v5, v123
	s_add_i32 s0, s0, s90
	s_add_u32 s2, s2, s22
	s_addc_u32 s3, s3, s23
	s_add_u32 s4, s4, s62
	s_addc_u32 s5, s5, s63
	s_cmp_lt_i32 s0, 0x10000
	s_cbranch_scc0 .Lcomb_nopf
	v_lshl_add_u64 v[124:125], s[4:5], 0, v[20:21]
	s_mov_b64 s[6:7], 0x64a2000
	v_lshl_add_u64 v[126:127], v[124:125], 0, s[6:7]
	s_mov_b64 s[6:7], 0x2f8a2000
	v_lshl_add_u64 v[128:129], v[124:125], 0, s[6:7]
	global_load_dwordx4 v[100:103], v[126:127], off
	global_load_dwordx4 v[104:107], v[126:127], off offset:16
	global_load_dwordx4 v[108:111], v[128:129], off
	global_load_dwordx4 v[112:115], v[128:129], off offset:16
	v_lshl_add_u64 v[124:125], s[2:3], 0, v[20:21]
	s_mov_b64 s[6:7], 0xe8a3800
	v_lshl_add_u64 v[124:125], v[124:125], 0, s[6:7]
	global_load_dwordx4 v[116:119], v[124:125], off
	global_load_dwordx4 v[120:123], v[124:125], off offset:16
.Lcomb_nopf:
	v_lshlrev_b32_e32 v24, 16, v37
	v_and_b32_e32 v25, 0xffff0000, v37
	v_lshlrev_b32_e32 v62, 16, v13
	v_lshlrev_b32_e32 v26, 16, v41
	v_and_b32_e32 v27, 0xffff0000, v41
	v_pk_add_f32 v[24:25], v[24:25], v[26:27]
	v_lshlrev_b32_e32 v26, 16, v36
	v_and_b32_e32 v27, 0xffff0000, v36
	v_lshlrev_b32_e32 v28, 16, v40
	v_and_b32_e32 v29, 0xffff0000, v40
	v_pk_add_f32 v[26:27], v[26:27], v[28:29]
	v_mov_b32_e32 v36, v25
	v_mov_b32_e32 v37, v27
	v_mov_b32_e32 v28, v24
	v_mov_b32_e32 v29, v26
	v_pk_mul_f32 v[36:37], v[36:37], v[36:37]
	v_lshlrev_b32_e32 v58, 16, v39
	v_pk_fma_f32 v[28:29], v[28:29], v[28:29], v[36:37]
	v_lshlrev_b32_e32 v36, 16, v4
	v_and_b32_e32 v37, 0xffff0000, v4
	v_mul_f32_e32 v4, 0xbfb8aa3b, v36
	v_exp_f32_e32 v4, v4
	v_and_b32_e32 v59, 0xffff0000, v39
	v_and_b32_e32 v63, 0xffff0000, v13
	v_mov_b32_e32 v40, v132
	v_mov_b32_e32 v41, v133
	v_mov_b32_e32 v42, v134
	v_mov_b32_e32 v43, v135
	v_mov_b32_e32 v44, v136
	v_mov_b32_e32 v45, v137
	v_mov_b32_e32 v46, v138
	v_mov_b32_e32 v47, v139
	v_mov_b32_e32 v48, v140
	v_mov_b32_e32 v49, v141
	v_mov_b32_e32 v50, v142
	v_mov_b32_e32 v51, v143
	v_mov_b32_e32 v52, v144
	v_mov_b32_e32 v53, v145
	v_mov_b32_e32 v54, v146
	v_mov_b32_e32 v55, v147
	v_add_f32_e32 v4, 1.0, v4
	v_rcp_f32_e32 v56, v4
	v_mul_f32_e32 v4, 0xbfb8aa3b, v37
	v_exp_f32_e32 v4, v4
	v_lshlrev_b32_e32 v68, 16, v15
	v_and_b32_e32 v69, 0xffff0000, v15
	v_lshlrev_b32_e32 v66, 16, v11
	v_add_f32_e32 v4, 1.0, v4
	v_rcp_f32_e32 v57, v4
	v_and_b32_e32 v67, 0xffff0000, v11
	v_pk_mul_f32 v[36:37], v[56:57], v[36:37]
	v_lshlrev_b32_e32 v56, 16, v35
	v_and_b32_e32 v57, 0xffff0000, v35
	v_pk_add_f32 v[56:57], v[56:57], v[58:59]
	v_lshlrev_b32_e32 v58, 16, v3
	v_and_b32_e32 v59, 0xffff0000, v3
	v_mul_f32_e32 v3, 0xbfb8aa3b, v58
	v_exp_f32_e32 v3, v3
	v_and_b32_e32 v35, 0xffff0000, v38
	v_add_f32_e32 v3, 1.0, v3
	v_rcp_f32_e32 v60, v3
	v_mul_f32_e32 v3, 0xbfb8aa3b, v59
	v_exp_f32_e32 v3, v3
	s_nop 0
	v_add_f32_e32 v3, 1.0, v3
	v_rcp_f32_e32 v61, v3
	s_nop 0
	v_pk_mul_f32 v[58:59], v[60:61], v[58:59]
	v_lshlrev_b32_e32 v60, 16, v34
	v_and_b32_e32 v61, 0xffff0000, v34
	v_lshlrev_b32_e32 v34, 16, v38
	v_pk_add_f32 v[34:35], v[60:61], v[34:35]
	v_mov_b32_e32 v60, v57
	v_mov_b32_e32 v61, v35
	v_mov_b32_e32 v38, v56
	v_mov_b32_e32 v39, v34
	v_pk_mul_f32 v[60:61], v[60:61], v[60:61]
	s_nop 0
	v_pk_fma_f32 v[38:39], v[38:39], v[38:39], v[60:61]
	v_lshlrev_b32_e32 v60, 16, v2
	v_and_b32_e32 v61, 0xffff0000, v2
	v_mul_f32_e32 v2, 0xbfb8aa3b, v60
	v_mul_f32_e32 v3, 0xbfb8aa3b, v61
	v_exp_f32_e32 v2, v2
	v_exp_f32_e32 v3, v3
	v_add_f32_e32 v2, 1.0, v2
	v_add_f32_e32 v3, 1.0, v3
	v_rcp_f32_e32 v2, v2
	v_rcp_f32_e32 v3, v3
	s_nop 0
	v_pk_mul_f32 v[2:3], v[2:3], v[60:61]
	v_lshlrev_b32_e32 v60, 16, v9
	v_and_b32_e32 v61, 0xffff0000, v9
	v_pk_add_f32 v[60:61], v[60:61], v[62:63]
	v_lshlrev_b32_e32 v62, 16, v17
	v_mul_f32_e32 v4, 0xbfb8aa3b, v62
	v_exp_f32_e32 v4, v4
	v_and_b32_e32 v63, 0xffff0000, v17
	v_and_b32_e32 v9, 0xffff0000, v12
	v_add_f32_e32 v4, 1.0, v4
	v_rcp_f32_e32 v64, v4
	v_mul_f32_e32 v4, 0xbfb8aa3b, v63
	v_exp_f32_e32 v4, v4
	s_nop 0
	v_add_f32_e32 v4, 1.0, v4
	v_rcp_f32_e32 v65, v4
	s_nop 0
	v_pk_mul_f32 v[62:63], v[64:65], v[62:63]
	v_lshlrev_b32_e32 v64, 16, v8
	v_and_b32_e32 v65, 0xffff0000, v8
	v_lshlrev_b32_e32 v8, 16, v12
	v_pk_add_f32 v[8:9], v[64:65], v[8:9]
	v_mov_b32_e32 v64, v61
	v_mov_b32_e32 v65, v9
	v_mov_b32_e32 v12, v60
	v_mov_b32_e32 v13, v8
	v_pk_mul_f32 v[64:65], v[64:65], v[64:65]
	s_nop 0
	v_pk_fma_f32 v[12:13], v[12:13], v[12:13], v[64:65]
	v_lshlrev_b32_e32 v64, 16, v16
	v_mul_f32_e32 v4, 0xbfb8aa3b, v64
	v_exp_f32_e32 v4, v4
	v_and_b32_e32 v65, 0xffff0000, v16
	v_add_f32_e32 v4, 1.0, v4
	v_rcp_f32_e32 v16, v4
	v_mul_f32_e32 v4, 0xbfb8aa3b, v65
	v_exp_f32_e32 v4, v4
	s_nop 0
	v_add_f32_e32 v4, 1.0, v4
	v_rcp_f32_e32 v17, v4
	v_mul_f32_e32 v4, 0xbfb8aa3b, v68
	v_exp_f32_e32 v4, v4
	v_pk_mul_f32 v[16:17], v[16:17], v[64:65]
	v_lshlrev_b32_e32 v64, 16, v7
	v_add_f32_e32 v4, 1.0, v4
	v_rcp_f32_e32 v70, v4
	v_mul_f32_e32 v4, 0xbfb8aa3b, v69
	v_exp_f32_e32 v4, v4
	v_and_b32_e32 v65, 0xffff0000, v7
	v_and_b32_e32 v7, 0xffff0000, v10
	v_pk_add_f32 v[64:65], v[64:65], v[66:67]
	v_add_f32_e32 v4, 1.0, v4
	v_rcp_f32_e32 v71, v4
	v_pk_mul_f32 v[66:67], v[64:65], v[64:65]
	v_pk_mul_f32 v[68:69], v[70:71], v[68:69]
	v_lshlrev_b32_e32 v70, 16, v6
	v_and_b32_e32 v71, 0xffff0000, v6
	v_lshlrev_b32_e32 v6, 16, v10
	v_pk_add_f32 v[6:7], v[70:71], v[6:7]
	v_lshlrev_b32_e32 v70, 16, v14
	v_mul_f32_e32 v4, 0xbfb8aa3b, v70
	v_exp_f32_e32 v4, v4
	v_and_b32_e32 v71, 0xffff0000, v14
	v_pk_mul_f32 v[10:11], v[6:7], v[6:7]
	v_add_f32_e32 v4, 1.0, v4
	v_rcp_f32_e32 v14, v4
	v_mul_f32_e32 v4, 0xbfb8aa3b, v71
	v_exp_f32_e32 v4, v4
	v_add_f32_e32 v10, v10, v11
	v_add_f32_e32 v4, 1.0, v4
	v_rcp_f32_e32 v15, v4
	v_add_f32_e32 v4, v66, v67
	v_add_f32_e32 v4, v10, v4
	v_add_f32_e32 v4, v13, v4
	v_add_f32_e32 v4, v12, v4
	v_add_f32_e32 v4, v39, v4
	v_add_f32_e32 v4, v38, v4
	v_add_f32_e32 v4, v29, v4
	v_add_f32_e32 v4, v28, v4
	ds_bpermute_b32 v10, v1, v4
	v_pk_mul_f32 v[14:15], v[14:15], v[70:71]
	s_waitcnt lgkmcnt(0)
	v_add_f32_e32 v4, v4, v10
	ds_bpermute_b32 v10, v30, v4
	s_waitcnt lgkmcnt(0)
	v_add_f32_e32 v4, v4, v10
	ds_bpermute_b32 v10, v31, v4
	s_waitcnt lgkmcnt(0)
	v_add_f32_e32 v4, v4, v10
	ds_bpermute_b32 v10, v32, v4
	s_waitcnt lgkmcnt(0)
	v_add_f32_e32 v4, v4, v10
	v_fmamk_f32 v4, v4, 0x3b800000, v206
	v_cmp_gt_f32_e32 vcc, s97, v4
	v_mul_f32_e32 v10, 0x4b800000, v4
	s_nop 0
	v_cndmask_b32_e32 v4, v4, v10, vcc
	v_rsq_f32_e32 v4, v4
	s_nop 0
	v_mul_f32_e32 v10, 0x45800000, v4
	v_cndmask_b32_e32 v10, v4, v10, vcc
	v_pk_mul_f32 v[6:7], v[6:7], v[10:11] op_sel_hi:[1,0]
	v_pk_mul_f32 v[12:13], v[64:65], v[10:11] op_sel_hi:[1,0]
	v_pk_mul_f32 v[6:7], v[52:53], v[6:7]
	v_pk_mul_f32 v[12:13], v[54:55], v[12:13]
	v_pk_mul_f32 v[6:7], v[14:15], v[6:7]
	v_pk_mul_f32 v[12:13], v[68:69], v[12:13]
	v_cvt_pk_bf16_f32 v6, v6, v7
	v_cvt_pk_bf16_f32 v7, v12, v13
	v_pk_mul_f32 v[8:9], v[8:9], v[10:11] op_sel_hi:[1,0]
	v_pk_mul_f32 v[12:13], v[60:61], v[10:11] op_sel_hi:[1,0]
	v_pk_mul_f32 v[8:9], v[48:49], v[8:9]
	v_pk_mul_f32 v[12:13], v[50:51], v[12:13]
	v_pk_mul_f32 v[8:9], v[16:17], v[8:9]
	v_pk_mul_f32 v[12:13], v[62:63], v[12:13]
	v_cvt_pk_bf16_f32 v8, v8, v9
	v_cvt_pk_bf16_f32 v9, v12, v13
	v_pk_mul_f32 v[12:13], v[34:35], v[10:11] op_sel_hi:[1,0]
	s_nop 0
	v_pk_mul_f32 v[12:13], v[44:45], v[12:13]
	s_nop 0
	v_pk_mul_f32 v[2:3], v[2:3], v[12:13]
	v_pk_mul_f32 v[12:13], v[56:57], v[10:11] op_sel_hi:[1,0]
	v_cvt_pk_bf16_f32 v2, v2, v3
	v_pk_mul_f32 v[12:13], v[46:47], v[12:13]
	s_nop 0
	v_pk_mul_f32 v[12:13], v[58:59], v[12:13]
	s_nop 0
	v_cvt_pk_bf16_f32 v3, v12, v13
	v_pk_mul_f32 v[12:13], v[26:27], v[10:11] op_sel_hi:[1,0]
	v_pk_mul_f32 v[10:11], v[24:25], v[10:11] op_sel_hi:[1,0]
	v_pk_mul_f32 v[12:13], v[40:41], v[12:13]
	v_pk_mul_f32 v[10:11], v[42:43], v[10:11]
	v_pk_mul_f32 v[12:13], v[36:37], v[12:13]
	s_nop 0
	v_cvt_pk_bf16_f32 v4, v12, v13
	v_lshlrev_b32_e32 v12, 16, v5
	v_and_b32_e32 v13, 0xffff0000, v5
	v_mul_f32_e32 v5, 0xbfb8aa3b, v12
	v_exp_f32_e32 v5, v5
	s_nop 0
	v_add_f32_e32 v5, 1.0, v5
	v_rcp_f32_e32 v14, v5
	v_mul_f32_e32 v5, 0xbfb8aa3b, v13
	v_exp_f32_e32 v5, v5
	s_nop 0
	v_add_f32_e32 v5, 1.0, v5
	v_rcp_f32_e32 v15, v5
	s_nop 0
	v_pk_mul_f32 v[12:13], v[14:15], v[12:13]
	s_nop 0
	v_pk_mul_f32 v[10:11], v[12:13], v[10:11]
	s_nop 0
	v_cvt_pk_bf16_f32 v5, v10, v11
	global_store_dwordx4 v[22:23], v[6:9], off
	global_store_dwordx4 v[22:23], v[2:5], off offset:16
	s_cbranch_scc1 .LBB0_1388
